# v33: v32 + GLA next-chunk global loads issued before barrier B1 (address math parked behind the barrier wait)
# speedup vs baseline: 1.0030x; 1.0030x over previous
; #define LAS __attribute__((address_space(3)))
; __device__ __forceinline__ unsigned pk_bf16(float lo, float hi) { f32x2 v; v.x = lo; v.y = hi; const bf16x2_t b = __builtin_convertvector(v, bf16x2_t); return __builtin_bit_cast(unsigned, b); }
; __device__ __forceinline__ void phase_gla(const Frame& F, int l, int gi, int ng, bool last, unsigned* cw) {
;     ...
;             *(LAS u32x4*)(lds + GL_RQ + (li * 136 + ls * 16) * 2) = pq0; *(LAS u32x4*)(lds + GL_RQ + (li * 136 + ls * 16 + 8) * 2) = pq1;
;             *(LAS u32x4*)(lds + GL_RK + (li * 136 + ls * 16) * 2) = pk0; *(LAS u32x4*)(lds + GL_RK + (li * 136 + ls * 16 + 8) * 2) = pk1;
;             *(LAS unsigned*)(lds + GL_LR + (li * 16 + ls * 2) * 2) = pk_f16(pg.x, pg.y);
;             { const f16x8 va = __builtin_bit_cast(f16x8, pv0), vb = __builtin_bit_cast(f16x8, pv1);
; #pragma unroll
;               for (int e = 0; e < 8; e += 2) { const unsigned pa = pk_bf16((float)va[e], (float)va[e + 1]), pb = pk_bf16((float)vb[e], (float)vb[e + 1]);
;                   *(LAS unsigned short*)(lds + GL_VT + ((vs * 16 + e) * 72 + vi) * 2) = (unsigned short)(pa & 0xffffu);
;                   *(LAS unsigned short*)(lds + GL_VT + ((vs * 16 + e + 1) * 72 + vi) * 2) = (unsigned short)(pa >> 16);
;                   *(LAS unsigned short*)(lds + GL_VT + ((vs * 16 + 8 + e) * 72 + vi) * 2) = (unsigned short)(pb & 0xffffu);
;                   *(LAS unsigned short*)(lds + GL_VT + ((vs * 16 + 8 + e + 1) * 72 + vi) * 2) = (unsigned short)(pb >> 16); } }
;             __syncthreads();
;             if (s + 1 < 68) GLA_LOAD(s + 1);
;             { const f16x8 ga = *(const LAS f16x8*)(lds + GL_LR + ((w >> 2) * 32 + r32) * 32 + hh * 16);
.LBB0_644:
	ds_write_b128 v137, v[70:73]
	ds_write_b128 v137, v[74:77] offset:16
	ds_write_b128 v137, v[82:85] offset:17408
	ds_write_b128 v137, v[78:81] offset:17424
	ds_write_b32 v138, v192 offset:34816
	s_add_i32 s14, s7, 4
	s_cmp_eq_u32 s7, 63
	ds_write_b16 v139, v184
	ds_write_b16_d16_hi v140, v184
	ds_write_b16 v141, v185
	ds_write_b16_d16_hi v142, v185
	ds_write_b16 v143, v186
	ds_write_b16_d16_hi v144, v186
	ds_write_b16 v145, v187
	ds_write_b16_d16_hi v146, v187
	ds_write_b16 v147, v188
	ds_write_b16_d16_hi v148, v188
	ds_write_b16 v149, v189
	ds_write_b16_d16_hi v150, v189
	ds_write_b16 v151, v190
	ds_write_b16_d16_hi v152, v190
	ds_write_b16 v153, v191
	ds_write_b16_d16_hi v154, v191
	s_cbranch_scc1 .Lgla_noload
	s_cmp_gt_u32 s14, 2
	s_cselect_b64 s[2:3], -1, 0
	s_mov_b64 s[12:13], -1
	s_and_b64 vcc, exec, s[2:3]
	s_cbranch_vccz .LBB0_647
	s_add_i32 s0, s7, 1
	s_and_b64 s[12:13], s[84:85], exec
	s_cselect_b32 s0, s0, s37
	s_mov_b64 s[12:13], 0

; #define LAS __attribute__((address_space(3)))
; __device__ __forceinline__ void phase_gla(const Frame& F, int l, int gi, int ng, bool last, unsigned* cw) {
;     ...
;             __syncthreads();
;             if (s + 1 < 68) GLA_LOAD(s + 1);
;             { const f16x8 ga = *(const LAS f16x8*)(lds + GL_LR + ((w >> 2) * 32 + r32) * 32 + hh * 16);
;               f32x16 la;
; #pragma unroll
;               for (int e = 0; e < 16; ++e) la[e] = 0.f;
;               la = __builtin_amdgcn_mfma_f32_32x32x16_f16(ga, gwf, la, 0, 0, 0);
.Lgla_noload:
	s_waitcnt lgkmcnt(0)
	s_barrier
	ds_read_b128 v[34:37], v155 offset:34816
	s_waitcnt lgkmcnt(0)
	v_mfma_f32_32x32x16_f16 v[34:49], v[34:37], v[66:69], 0
	s_nop 11
